# setup phases: sC staging loops (phase-0 silu(c), phase-1 shift vectors) and the per-layer XCC placement check: serialized load-wait iterations replaced by batched loads with counted waits
# speedup vs baseline: 1.0073x; 1.0073x over previous
; #define LAS __attribute__((address_space(3)))
; __global__ void __launch_bounds__(NTHR, 2) mega_fwd(Params P0) {
;     ...
;                 { const unsigned* tk = (const unsigned*)(ws + WS_CTL) + 8192; bool even = true;
; #pragma unroll
;                   for (int x = 0; x < 8; ++x) even = even && (__hip_atomic_load(tk + 64 * x, __ATOMIC_RELAXED, __HIP_MEMORY_SCOPE_AGENT) == 32u);
;                   if (even) { volatile LAS unsigned* misc = (volatile LAS unsigned*)(lds + RING_BYTES + 320); slot = (int)misc[16]; xcd = (int)misc[17]; } }
.LBB0_375:
	s_andn2_b64 vcc, exec, s[2:3]
	s_cbranch_vccnz .LBB0_429
	v_readlane_b32 s5, v254, 0
	s_mov_b32 s4, s5
	v_mov_b32_e32 v0, 0x3ed08000
	global_load_dword v240, v0, s[92:93] sc1
	global_load_dword v241, v0, s[92:93] offset:256 sc1
	global_load_dword v242, v0, s[92:93] offset:512 sc1
	global_load_dword v243, v0, s[92:93] offset:768 sc1
	global_load_dword v244, v0, s[92:93] offset:1024 sc1
	global_load_dword v245, v0, s[92:93] offset:1280 sc1
	global_load_dword v246, v0, s[92:93] offset:1536 sc1
	global_load_dword v247, v0, s[92:93] offset:1792 sc1
	s_waitcnt vmcnt(0)
	v_xor_b32_e32 v240, 32, v240
	v_xor_b32_e32 v241, 32, v241
	v_xor_b32_e32 v242, 32, v242
	v_xor_b32_e32 v243, 32, v243
	v_xor_b32_e32 v244, 32, v244
	v_xor_b32_e32 v245, 32, v245
	v_xor_b32_e32 v246, 32, v246
	v_xor_b32_e32 v247, 32, v247
	v_or3_b32 v240, v240, v241, v242
	v_or3_b32 v243, v243, v244, v245
	v_or3_b32 v240, v240, v243, v246
	v_or_b32_e32 v240, v240, v247
	v_cmp_eq_u32_e64 s[2:3], 0, v240

; __device__ __forceinline__ int obid() { int b = (int)blockIdx.x; asm volatile("" : "+s"(b)); return b; }
; __device__ __forceinline__ void bias_phase(const Params& P, LAS unsigned char* lds, int G) {
;     ...
;     for (int it = obid(); it < 4 * 152; it += G) { const int l = it / 152, blk = it % 152; const bool ffn = blk >= 64; const int R0 = (ffn ? blk - 64 : blk) * 64;
;         __syncthreads();
;         for (int i = tid; i < 16 * 1024; i += NTHR) sC[i] = MOD[((size_t)l * 16 + (i >> 10)) * 6144 + (ffn ? 3072 : 0) + (i & 1023)];
;         __syncthreads();
.LBB0_624:
	s_mul_hi_i32 s6, s4, 0x6bca1af3
	s_lshr_b32 s7, s6, 31
	s_ashr_i32 s6, s6, 6
	s_add_i32 s8, s6, s7
	s_mul_i32 s6, s8, 0x98
	s_sub_i32 s52, s4, s6
	s_cmp_gt_i32 s52, 63
	s_cselect_b64 s[14:15], -1, 0
	s_cmp_lt_i32 s52, 64
	s_cselect_b64 s[6:7], -1, 0
	s_waitcnt vmcnt(0)
	s_barrier
	s_and_saveexec_b64 s[10:11], s[40:41]
	s_cbranch_execz .LBB0_634
	s_ashr_i32 s9, s8, 31
	s_lshl_b64 s[12:13], s[8:9], 4
	s_and_b64 s[16:17], s[14:15], exec
	s_cselect_b32 s9, 0x3000, 0
	s_add_u32 s16, s5, s9
	s_addc_u32 s17, s30, 0
	s_mul_i32 s18, s12, 0x6000
	s_mul_hi_u32 s19, s12, 0x6000
	s_add_u32 s16, s16, s18
	s_addc_u32 s17, s17, s19
	v_mov_b32_e32 v194, v95
	global_load_dword v162, v194, s[16:17]
	global_load_dword v163, v194, s[16:17] offset:2048
	v_add_u32_e32 v194, 0x6000, v194
	global_load_dword v164, v194, s[16:17]
	global_load_dword v165, v194, s[16:17] offset:2048
	v_add_u32_e32 v194, 0x6000, v194
	global_load_dword v166, v194, s[16:17]
	global_load_dword v167, v194, s[16:17] offset:2048
	v_add_u32_e32 v194, 0x6000, v194
	global_load_dword v168, v194, s[16:17]
	global_load_dword v169, v194, s[16:17] offset:2048
	v_add_u32_e32 v194, 0x6000, v194
	global_load_dword v170, v194, s[16:17]
	global_load_dword v171, v194, s[16:17] offset:2048
	v_add_u32_e32 v194, 0x6000, v194
	global_load_dword v172, v194, s[16:17]
	global_load_dword v173, v194, s[16:17] offset:2048
	v_add_u32_e32 v194, 0x6000, v194
	global_load_dword v174, v194, s[16:17]
	global_load_dword v175, v194, s[16:17] offset:2048
	v_add_u32_e32 v194, 0x6000, v194
	global_load_dword v176, v194, s[16:17]
	global_load_dword v177, v194, s[16:17] offset:2048
	v_add_u32_e32 v194, 0x6000, v194
	global_load_dword v178, v194, s[16:17]
	global_load_dword v179, v194, s[16:17] offset:2048
	v_add_u32_e32 v194, 0x6000, v194
	global_load_dword v180, v194, s[16:17]
	global_load_dword v181, v194, s[16:17] offset:2048
	v_add_u32_e32 v194, 0x6000, v194
	global_load_dword v182, v194, s[16:17]
	global_load_dword v183, v194, s[16:17] offset:2048
	v_add_u32_e32 v194, 0x6000, v194
	global_load_dword v184, v194, s[16:17]
	global_load_dword v185, v194, s[16:17] offset:2048
	v_add_u32_e32 v194, 0x6000, v194
	global_load_dword v186, v194, s[16:17]
	global_load_dword v187, v194, s[16:17] offset:2048
	v_add_u32_e32 v194, 0x6000, v194
	global_load_dword v188, v194, s[16:17]
	global_load_dword v189, v194, s[16:17] offset:2048
	v_add_u32_e32 v194, 0x6000, v194
	global_load_dword v190, v194, s[16:17]
	global_load_dword v191, v194, s[16:17] offset:2048
	v_add_u32_e32 v194, 0x6000, v194
	global_load_dword v192, v194, s[16:17]
	global_load_dword v193, v194, s[16:17] offset:2048
	s_waitcnt vmcnt(30)
	ds_write2st64_b32 v96, v162, v163 offset1:8
	s_waitcnt vmcnt(28)
	ds_write2st64_b32 v96, v164, v165 offset0:16 offset1:24
	s_waitcnt vmcnt(26)
	ds_write2st64_b32 v96, v166, v167 offset0:32 offset1:40
	s_waitcnt vmcnt(24)
	ds_write2st64_b32 v96, v168, v169 offset0:48 offset1:56
	s_waitcnt vmcnt(22)
	ds_write2st64_b32 v96, v170, v171 offset0:64 offset1:72
	s_waitcnt vmcnt(20)
	ds_write2st64_b32 v96, v172, v173 offset0:80 offset1:88
	s_waitcnt vmcnt(18)
	ds_write2st64_b32 v96, v174, v175 offset0:96 offset1:104
	s_waitcnt vmcnt(16)
	ds_write2st64_b32 v96, v176, v177 offset0:112 offset1:120
	s_waitcnt vmcnt(14)
	ds_write2st64_b32 v96, v178, v179 offset0:128 offset1:136
	s_waitcnt vmcnt(12)
	ds_write2st64_b32 v96, v180, v181 offset0:144 offset1:152
	s_waitcnt vmcnt(10)
	ds_write2st64_b32 v96, v182, v183 offset0:160 offset1:168
	s_waitcnt vmcnt(8)
	ds_write2st64_b32 v96, v184, v185 offset0:176 offset1:184
	s_waitcnt vmcnt(6)
	ds_write2st64_b32 v96, v186, v187 offset0:192 offset1:200
	s_waitcnt vmcnt(4)
	ds_write2st64_b32 v96, v188, v189 offset0:208 offset1:216
	s_waitcnt vmcnt(2)
	ds_write2st64_b32 v96, v190, v191 offset0:224 offset1:232
	s_waitcnt vmcnt(0)
	ds_write2st64_b32 v96, v192, v193 offset0:240 offset1:248

; __device__ __forceinline__ void phase0(const Params& P, LAS unsigned char* lds, int G) {
;     ...
;     for (int i = tid; i < 16 * 1024; i += NTHR) { const float v = P.c[i]; sC[i] = v / (1.0f + __expf(-v)); }
.LBB0_839:
	s_or_b64 exec, exec, s[4:5]
	s_movk_i32 s3, 0x4000
	v_cmp_gt_i32_e32 vcc, s3, v66
	s_and_saveexec_b64 s[4:5], vcc
	s_cbranch_execz .LBB0_842
	v_readlane_b32 s6, v255, 29
	v_readlane_b32 s7, v255, 30
	s_load_dwordx2 s[6:7], s[6:7], 0x8
	v_ashrrev_i32_e32 v67, 31, v66
	v_add_u32_e32 v0, 0xfffffe00, v66
	v_lshl_add_u32 v4, v66, 2, 0
	s_waitcnt lgkmcnt(0)
	v_lshl_add_u64 v[2:3], v[66:67], 2, s[6:7]
	v_mov_b32_e32 v194, v2
	v_mov_b32_e32 v195, v3
	global_load_dword v162, v[194:195], off
	global_load_dword v163, v[194:195], off offset:2048
	v_lshl_add_u64 v[194:195], v[194:195], 0, s[88:89]
	v_lshl_add_u64 v[194:195], v[194:195], 0, s[88:89]
	global_load_dword v164, v[194:195], off
	global_load_dword v165, v[194:195], off offset:2048
	v_lshl_add_u64 v[194:195], v[194:195], 0, s[88:89]
	v_lshl_add_u64 v[194:195], v[194:195], 0, s[88:89]
	global_load_dword v166, v[194:195], off
	global_load_dword v167, v[194:195], off offset:2048
	v_lshl_add_u64 v[194:195], v[194:195], 0, s[88:89]
	v_lshl_add_u64 v[194:195], v[194:195], 0, s[88:89]
	global_load_dword v168, v[194:195], off
	global_load_dword v169, v[194:195], off offset:2048
	v_lshl_add_u64 v[194:195], v[194:195], 0, s[88:89]
	v_lshl_add_u64 v[194:195], v[194:195], 0, s[88:89]
	global_load_dword v170, v[194:195], off
	global_load_dword v171, v[194:195], off offset:2048
	v_lshl_add_u64 v[194:195], v[194:195], 0, s[88:89]
	v_lshl_add_u64 v[194:195], v[194:195], 0, s[88:89]
	global_load_dword v172, v[194:195], off
	global_load_dword v173, v[194:195], off offset:2048
	v_lshl_add_u64 v[194:195], v[194:195], 0, s[88:89]
	v_lshl_add_u64 v[194:195], v[194:195], 0, s[88:89]
	global_load_dword v174, v[194:195], off
	global_load_dword v175, v[194:195], off offset:2048
	v_lshl_add_u64 v[194:195], v[194:195], 0, s[88:89]
	v_lshl_add_u64 v[194:195], v[194:195], 0, s[88:89]
	global_load_dword v176, v[194:195], off
	global_load_dword v177, v[194:195], off offset:2048
	v_lshl_add_u64 v[194:195], v[194:195], 0, s[88:89]
	v_lshl_add_u64 v[194:195], v[194:195], 0, s[88:89]
	global_load_dword v178, v[194:195], off
	global_load_dword v179, v[194:195], off offset:2048
	v_lshl_add_u64 v[194:195], v[194:195], 0, s[88:89]
	v_lshl_add_u64 v[194:195], v[194:195], 0, s[88:89]
	global_load_dword v180, v[194:195], off
	global_load_dword v181, v[194:195], off offset:2048
	v_lshl_add_u64 v[194:195], v[194:195], 0, s[88:89]
	v_lshl_add_u64 v[194:195], v[194:195], 0, s[88:89]
	global_load_dword v182, v[194:195], off
	global_load_dword v183, v[194:195], off offset:2048
	v_lshl_add_u64 v[194:195], v[194:195], 0, s[88:89]
	v_lshl_add_u64 v[194:195], v[194:195], 0, s[88:89]
	global_load_dword v184, v[194:195], off
	global_load_dword v185, v[194:195], off offset:2048
	v_lshl_add_u64 v[194:195], v[194:195], 0, s[88:89]
	v_lshl_add_u64 v[194:195], v[194:195], 0, s[88:89]
	global_load_dword v186, v[194:195], off
	global_load_dword v187, v[194:195], off offset:2048
	v_lshl_add_u64 v[194:195], v[194:195], 0, s[88:89]
	v_lshl_add_u64 v[194:195], v[194:195], 0, s[88:89]
	global_load_dword v188, v[194:195], off
	global_load_dword v189, v[194:195], off offset:2048
	v_lshl_add_u64 v[194:195], v[194:195], 0, s[88:89]
	v_lshl_add_u64 v[194:195], v[194:195], 0, s[88:89]
	global_load_dword v190, v[194:195], off
	global_load_dword v191, v[194:195], off offset:2048
	v_lshl_add_u64 v[194:195], v[194:195], 0, s[88:89]
	v_lshl_add_u64 v[194:195], v[194:195], 0, s[88:89]
	global_load_dword v192, v[194:195], off
	global_load_dword v193, v[194:195], off offset:2048
	s_waitcnt vmcnt(31)
	v_mov_b32_e32 v5, v162
	v_mul_f32_e32 v6, 0xbfb8aa3b, v5
	v_exp_f32_e32 v6, v6
	s_nop 0
	v_add_f32_e32 v6, 1.0, v6
	v_div_scale_f32 v7, s[8:9], v6, v6, v5
	v_rcp_f32_e32 v8, v7
	v_div_scale_f32 v9, vcc, v5, v6, v5
	v_fma_f32 v10, -v7, v8, 1.0
	v_fmac_f32_e32 v8, v10, v8
	v_mul_f32_e32 v10, v9, v8
	v_fma_f32 v11, -v7, v10, v9
	v_fmac_f32_e32 v10, v11, v8
	v_fma_f32 v7, -v7, v10, v9
	v_div_fmas_f32 v7, v7, v8, v10
	v_div_fixup_f32 v5, v7, v6, v5
	ds_write_b32 v4, v5
	s_waitcnt vmcnt(30)
	v_mov_b32_e32 v5, v163
	v_mul_f32_e32 v6, 0xbfb8aa3b, v5
	v_exp_f32_e32 v6, v6
	s_nop 0
	v_add_f32_e32 v6, 1.0, v6
	v_div_scale_f32 v7, s[8:9], v6, v6, v5
	v_rcp_f32_e32 v8, v7
	v_div_scale_f32 v9, vcc, v5, v6, v5
	v_fma_f32 v10, -v7, v8, 1.0
	v_fmac_f32_e32 v8, v10, v8
	v_mul_f32_e32 v10, v9, v8
	v_fma_f32 v11, -v7, v10, v9
	v_fmac_f32_e32 v10, v11, v8
	v_fma_f32 v7, -v7, v10, v9
	v_div_fmas_f32 v7, v7, v8, v10
	v_div_fixup_f32 v5, v7, v6, v5
	ds_write_b32 v4, v5 offset:2048
	s_waitcnt vmcnt(29)
	v_mov_b32_e32 v5, v164
	v_mul_f32_e32 v6, 0xbfb8aa3b, v5
	v_exp_f32_e32 v6, v6
	s_nop 0
	v_add_f32_e32 v6, 1.0, v6
	v_div_scale_f32 v7, s[8:9], v6, v6, v5
	v_rcp_f32_e32 v8, v7
	v_div_scale_f32 v9, vcc, v5, v6, v5
	v_fma_f32 v10, -v7, v8, 1.0
	v_fmac_f32_e32 v8, v10, v8
	v_mul_f32_e32 v10, v9, v8
	v_fma_f32 v11, -v7, v10, v9
	v_fmac_f32_e32 v10, v11, v8
	v_fma_f32 v7, -v7, v10, v9
	v_div_fmas_f32 v7, v7, v8, v10
	v_div_fixup_f32 v5, v7, v6, v5
	ds_write_b32 v4, v5 offset:4096
	s_waitcnt vmcnt(28)
	v_mov_b32_e32 v5, v165
	v_mul_f32_e32 v6, 0xbfb8aa3b, v5
	v_exp_f32_e32 v6, v6
	s_nop 0
	v_add_f32_e32 v6, 1.0, v6
	v_div_scale_f32 v7, s[8:9], v6, v6, v5
	v_rcp_f32_e32 v8, v7
	v_div_scale_f32 v9, vcc, v5, v6, v5
	v_fma_f32 v10, -v7, v8, 1.0
	v_fmac_f32_e32 v8, v10, v8
	v_mul_f32_e32 v10, v9, v8
	v_fma_f32 v11, -v7, v10, v9
	v_fmac_f32_e32 v10, v11, v8
	v_fma_f32 v7, -v7, v10, v9
	v_div_fmas_f32 v7, v7, v8, v10
	v_div_fixup_f32 v5, v7, v6, v5
	ds_write_b32 v4, v5 offset:6144
	s_waitcnt vmcnt(27)
; __device__ __forceinline__ void phase0(const Params& P, LAS unsigned char* lds, int G) {
;     ...
;     for (int i = tid; i < 16 * 1024; i += NTHR) { const float v = P.c[i]; sC[i] = v / (1.0f + __expf(-v)); }
	v_mov_b32_e32 v5, v166
	v_mul_f32_e32 v6, 0xbfb8aa3b, v5
	v_exp_f32_e32 v6, v6
	s_nop 0
	v_add_f32_e32 v6, 1.0, v6
	v_div_scale_f32 v7, s[8:9], v6, v6, v5
	v_rcp_f32_e32 v8, v7
	v_div_scale_f32 v9, vcc, v5, v6, v5
	v_fma_f32 v10, -v7, v8, 1.0
	v_fmac_f32_e32 v8, v10, v8
	v_mul_f32_e32 v10, v9, v8
	v_fma_f32 v11, -v7, v10, v9
	v_fmac_f32_e32 v10, v11, v8
	v_fma_f32 v7, -v7, v10, v9
	v_div_fmas_f32 v7, v7, v8, v10
	v_div_fixup_f32 v5, v7, v6, v5
	ds_write_b32 v4, v5 offset:8192
	s_waitcnt vmcnt(26)
	v_mov_b32_e32 v5, v167
	v_mul_f32_e32 v6, 0xbfb8aa3b, v5
	v_exp_f32_e32 v6, v6
	s_nop 0
	v_add_f32_e32 v6, 1.0, v6
	v_div_scale_f32 v7, s[8:9], v6, v6, v5
	v_rcp_f32_e32 v8, v7
	v_div_scale_f32 v9, vcc, v5, v6, v5
	v_fma_f32 v10, -v7, v8, 1.0
	v_fmac_f32_e32 v8, v10, v8
	v_mul_f32_e32 v10, v9, v8
	v_fma_f32 v11, -v7, v10, v9
	v_fmac_f32_e32 v10, v11, v8
	v_fma_f32 v7, -v7, v10, v9
	v_div_fmas_f32 v7, v7, v8, v10
	v_div_fixup_f32 v5, v7, v6, v5
	ds_write_b32 v4, v5 offset:10240
	s_waitcnt vmcnt(25)
	v_mov_b32_e32 v5, v168
	v_mul_f32_e32 v6, 0xbfb8aa3b, v5
	v_exp_f32_e32 v6, v6
	s_nop 0
	v_add_f32_e32 v6, 1.0, v6
	v_div_scale_f32 v7, s[8:9], v6, v6, v5
	v_rcp_f32_e32 v8, v7
	v_div_scale_f32 v9, vcc, v5, v6, v5
	v_fma_f32 v10, -v7, v8, 1.0
	v_fmac_f32_e32 v8, v10, v8
	v_mul_f32_e32 v10, v9, v8
	v_fma_f32 v11, -v7, v10, v9
	v_fmac_f32_e32 v10, v11, v8
	v_fma_f32 v7, -v7, v10, v9
	v_div_fmas_f32 v7, v7, v8, v10
	v_div_fixup_f32 v5, v7, v6, v5
	ds_write_b32 v4, v5 offset:12288
	s_waitcnt vmcnt(24)
	v_mov_b32_e32 v5, v169
	v_mul_f32_e32 v6, 0xbfb8aa3b, v5
	v_exp_f32_e32 v6, v6
	s_nop 0
	v_add_f32_e32 v6, 1.0, v6
	v_div_scale_f32 v7, s[8:9], v6, v6, v5
	v_rcp_f32_e32 v8, v7
	v_div_scale_f32 v9, vcc, v5, v6, v5
	v_fma_f32 v10, -v7, v8, 1.0
	v_fmac_f32_e32 v8, v10, v8
	v_mul_f32_e32 v10, v9, v8
	v_fma_f32 v11, -v7, v10, v9
	v_fmac_f32_e32 v10, v11, v8
	v_fma_f32 v7, -v7, v10, v9
	v_div_fmas_f32 v7, v7, v8, v10
	v_div_fixup_f32 v5, v7, v6, v5
	ds_write_b32 v4, v5 offset:14336
	s_waitcnt vmcnt(23)
	v_mov_b32_e32 v5, v170
	v_mul_f32_e32 v6, 0xbfb8aa3b, v5
	v_exp_f32_e32 v6, v6
	s_nop 0
	v_add_f32_e32 v6, 1.0, v6
	v_div_scale_f32 v7, s[8:9], v6, v6, v5
	v_rcp_f32_e32 v8, v7
	v_div_scale_f32 v9, vcc, v5, v6, v5
	v_fma_f32 v10, -v7, v8, 1.0
	v_fmac_f32_e32 v8, v10, v8
	v_mul_f32_e32 v10, v9, v8
	v_fma_f32 v11, -v7, v10, v9
	v_fmac_f32_e32 v10, v11, v8
	v_fma_f32 v7, -v7, v10, v9
	v_div_fmas_f32 v7, v7, v8, v10
	v_div_fixup_f32 v5, v7, v6, v5
	ds_write_b32 v4, v5 offset:16384
	s_waitcnt vmcnt(22)
	v_mov_b32_e32 v5, v171
	v_mul_f32_e32 v6, 0xbfb8aa3b, v5
	v_exp_f32_e32 v6, v6
	s_nop 0
	v_add_f32_e32 v6, 1.0, v6
	v_div_scale_f32 v7, s[8:9], v6, v6, v5
	v_rcp_f32_e32 v8, v7
	v_div_scale_f32 v9, vcc, v5, v6, v5
	v_fma_f32 v10, -v7, v8, 1.0
	v_fmac_f32_e32 v8, v10, v8
	v_mul_f32_e32 v10, v9, v8
	v_fma_f32 v11, -v7, v10, v9
	v_fmac_f32_e32 v10, v11, v8
	v_fma_f32 v7, -v7, v10, v9
	v_div_fmas_f32 v7, v7, v8, v10
	v_div_fixup_f32 v5, v7, v6, v5
	ds_write_b32 v4, v5 offset:18432
	s_waitcnt vmcnt(21)
	v_mov_b32_e32 v5, v172
	v_mul_f32_e32 v6, 0xbfb8aa3b, v5
	v_exp_f32_e32 v6, v6
	s_nop 0
	v_add_f32_e32 v6, 1.0, v6
	v_div_scale_f32 v7, s[8:9], v6, v6, v5
	v_rcp_f32_e32 v8, v7
	v_div_scale_f32 v9, vcc, v5, v6, v5
	v_fma_f32 v10, -v7, v8, 1.0
	v_fmac_f32_e32 v8, v10, v8
	v_mul_f32_e32 v10, v9, v8
	v_fma_f32 v11, -v7, v10, v9
	v_fmac_f32_e32 v10, v11, v8
	v_fma_f32 v7, -v7, v10, v9
	v_div_fmas_f32 v7, v7, v8, v10
	v_div_fixup_f32 v5, v7, v6, v5
	ds_write_b32 v4, v5 offset:20480
	s_waitcnt vmcnt(20)
	v_mov_b32_e32 v5, v173
	v_mul_f32_e32 v6, 0xbfb8aa3b, v5
	v_exp_f32_e32 v6, v6
	s_nop 0
	v_add_f32_e32 v6, 1.0, v6
	v_div_scale_f32 v7, s[8:9], v6, v6, v5
	v_rcp_f32_e32 v8, v7
	v_div_scale_f32 v9, vcc, v5, v6, v5
	v_fma_f32 v10, -v7, v8, 1.0
	v_fmac_f32_e32 v8, v10, v8
	v_mul_f32_e32 v10, v9, v8
	v_fma_f32 v11, -v7, v10, v9
	v_fmac_f32_e32 v10, v11, v8
	v_fma_f32 v7, -v7, v10, v9
	v_div_fmas_f32 v7, v7, v8, v10
	v_div_fixup_f32 v5, v7, v6, v5
	ds_write_b32 v4, v5 offset:22528
	s_waitcnt vmcnt(19)
	v_mov_b32_e32 v5, v174
	v_mul_f32_e32 v6, 0xbfb8aa3b, v5
	v_exp_f32_e32 v6, v6
	s_nop 0
	v_add_f32_e32 v6, 1.0, v6
	v_div_scale_f32 v7, s[8:9], v6, v6, v5
	v_rcp_f32_e32 v8, v7
	v_div_scale_f32 v9, vcc, v5, v6, v5
	v_fma_f32 v10, -v7, v8, 1.0
	v_fmac_f32_e32 v8, v10, v8
	v_mul_f32_e32 v10, v9, v8
	v_fma_f32 v11, -v7, v10, v9
	v_fmac_f32_e32 v10, v11, v8
	v_fma_f32 v7, -v7, v10, v9
	v_div_fmas_f32 v7, v7, v8, v10
	v_div_fixup_f32 v5, v7, v6, v5
	ds_write_b32 v4, v5 offset:24576
	s_waitcnt vmcnt(18)
	v_mov_b32_e32 v5, v175
	v_mul_f32_e32 v6, 0xbfb8aa3b, v5
	v_exp_f32_e32 v6, v6
	s_nop 0
	v_add_f32_e32 v6, 1.0, v6
	v_div_scale_f32 v7, s[8:9], v6, v6, v5
	v_rcp_f32_e32 v8, v7
	v_div_scale_f32 v9, vcc, v5, v6, v5
	v_fma_f32 v10, -v7, v8, 1.0
	v_fmac_f32_e32 v8, v10, v8
	v_mul_f32_e32 v10, v9, v8
	v_fma_f32 v11, -v7, v10, v9
	v_fmac_f32_e32 v10, v11, v8
	v_fma_f32 v7, -v7, v10, v9
	v_div_fmas_f32 v7, v7, v8, v10
	v_div_fixup_f32 v5, v7, v6, v5
	ds_write_b32 v4, v5 offset:26624
	s_waitcnt vmcnt(17)
	v_mov_b32_e32 v5, v176
	v_mul_f32_e32 v6, 0xbfb8aa3b, v5
	v_exp_f32_e32 v6, v6
	s_nop 0
	v_add_f32_e32 v6, 1.0, v6
	v_div_scale_f32 v7, s[8:9], v6, v6, v5
	v_rcp_f32_e32 v8, v7
	v_div_scale_f32 v9, vcc, v5, v6, v5
	v_fma_f32 v10, -v7, v8, 1.0
	v_fmac_f32_e32 v8, v10, v8
	v_mul_f32_e32 v10, v9, v8
	v_fma_f32 v11, -v7, v10, v9
	v_fmac_f32_e32 v10, v11, v8
	v_fma_f32 v7, -v7, v10, v9
	v_div_fmas_f32 v7, v7, v8, v10
	v_div_fixup_f32 v5, v7, v6, v5
	ds_write_b32 v4, v5 offset:28672
	s_waitcnt vmcnt(16)
; __device__ __forceinline__ void phase0(const Params& P, LAS unsigned char* lds, int G) {
;     ...
;     for (int i = tid; i < 16 * 1024; i += NTHR) { const float v = P.c[i]; sC[i] = v / (1.0f + __expf(-v)); }
	v_mov_b32_e32 v5, v177
	v_mul_f32_e32 v6, 0xbfb8aa3b, v5
	v_exp_f32_e32 v6, v6
	s_nop 0
	v_add_f32_e32 v6, 1.0, v6
	v_div_scale_f32 v7, s[8:9], v6, v6, v5
	v_rcp_f32_e32 v8, v7
	v_div_scale_f32 v9, vcc, v5, v6, v5
	v_fma_f32 v10, -v7, v8, 1.0
	v_fmac_f32_e32 v8, v10, v8
	v_mul_f32_e32 v10, v9, v8
	v_fma_f32 v11, -v7, v10, v9
	v_fmac_f32_e32 v10, v11, v8
	v_fma_f32 v7, -v7, v10, v9
	v_div_fmas_f32 v7, v7, v8, v10
	v_div_fixup_f32 v5, v7, v6, v5
	ds_write_b32 v4, v5 offset:30720
	s_waitcnt vmcnt(15)
	v_mov_b32_e32 v5, v178
	v_mul_f32_e32 v6, 0xbfb8aa3b, v5
	v_exp_f32_e32 v6, v6
	s_nop 0
	v_add_f32_e32 v6, 1.0, v6
	v_div_scale_f32 v7, s[8:9], v6, v6, v5
	v_rcp_f32_e32 v8, v7
	v_div_scale_f32 v9, vcc, v5, v6, v5
	v_fma_f32 v10, -v7, v8, 1.0
	v_fmac_f32_e32 v8, v10, v8
	v_mul_f32_e32 v10, v9, v8
	v_fma_f32 v11, -v7, v10, v9
	v_fmac_f32_e32 v10, v11, v8
	v_fma_f32 v7, -v7, v10, v9
	v_div_fmas_f32 v7, v7, v8, v10
	v_div_fixup_f32 v5, v7, v6, v5
	ds_write_b32 v4, v5 offset:32768
	s_waitcnt vmcnt(14)
	v_mov_b32_e32 v5, v179
	v_mul_f32_e32 v6, 0xbfb8aa3b, v5
	v_exp_f32_e32 v6, v6
	s_nop 0
	v_add_f32_e32 v6, 1.0, v6
	v_div_scale_f32 v7, s[8:9], v6, v6, v5
	v_rcp_f32_e32 v8, v7
	v_div_scale_f32 v9, vcc, v5, v6, v5
	v_fma_f32 v10, -v7, v8, 1.0
	v_fmac_f32_e32 v8, v10, v8
	v_mul_f32_e32 v10, v9, v8
	v_fma_f32 v11, -v7, v10, v9
	v_fmac_f32_e32 v10, v11, v8
	v_fma_f32 v7, -v7, v10, v9
	v_div_fmas_f32 v7, v7, v8, v10
	v_div_fixup_f32 v5, v7, v6, v5
	ds_write_b32 v4, v5 offset:34816
	s_waitcnt vmcnt(13)
	v_mov_b32_e32 v5, v180
	v_mul_f32_e32 v6, 0xbfb8aa3b, v5
	v_exp_f32_e32 v6, v6
	s_nop 0
	v_add_f32_e32 v6, 1.0, v6
	v_div_scale_f32 v7, s[8:9], v6, v6, v5
	v_rcp_f32_e32 v8, v7
	v_div_scale_f32 v9, vcc, v5, v6, v5
	v_fma_f32 v10, -v7, v8, 1.0
	v_fmac_f32_e32 v8, v10, v8
	v_mul_f32_e32 v10, v9, v8
	v_fma_f32 v11, -v7, v10, v9
	v_fmac_f32_e32 v10, v11, v8
	v_fma_f32 v7, -v7, v10, v9
	v_div_fmas_f32 v7, v7, v8, v10
	v_div_fixup_f32 v5, v7, v6, v5
	ds_write_b32 v4, v5 offset:36864
	s_waitcnt vmcnt(12)
	v_mov_b32_e32 v5, v181
	v_mul_f32_e32 v6, 0xbfb8aa3b, v5
	v_exp_f32_e32 v6, v6
	s_nop 0
	v_add_f32_e32 v6, 1.0, v6
	v_div_scale_f32 v7, s[8:9], v6, v6, v5
	v_rcp_f32_e32 v8, v7
	v_div_scale_f32 v9, vcc, v5, v6, v5
	v_fma_f32 v10, -v7, v8, 1.0
	v_fmac_f32_e32 v8, v10, v8
	v_mul_f32_e32 v10, v9, v8
	v_fma_f32 v11, -v7, v10, v9
	v_fmac_f32_e32 v10, v11, v8
	v_fma_f32 v7, -v7, v10, v9
	v_div_fmas_f32 v7, v7, v8, v10
	v_div_fixup_f32 v5, v7, v6, v5
	ds_write_b32 v4, v5 offset:38912
	s_waitcnt vmcnt(11)
	v_mov_b32_e32 v5, v182
	v_mul_f32_e32 v6, 0xbfb8aa3b, v5
	v_exp_f32_e32 v6, v6
	s_nop 0
	v_add_f32_e32 v6, 1.0, v6
	v_div_scale_f32 v7, s[8:9], v6, v6, v5
	v_rcp_f32_e32 v8, v7
	v_div_scale_f32 v9, vcc, v5, v6, v5
	v_fma_f32 v10, -v7, v8, 1.0
	v_fmac_f32_e32 v8, v10, v8
	v_mul_f32_e32 v10, v9, v8
	v_fma_f32 v11, -v7, v10, v9
	v_fmac_f32_e32 v10, v11, v8
	v_fma_f32 v7, -v7, v10, v9
	v_div_fmas_f32 v7, v7, v8, v10
	v_div_fixup_f32 v5, v7, v6, v5
	ds_write_b32 v4, v5 offset:40960
	s_waitcnt vmcnt(10)
	v_mov_b32_e32 v5, v183
	v_mul_f32_e32 v6, 0xbfb8aa3b, v5
	v_exp_f32_e32 v6, v6
	s_nop 0
	v_add_f32_e32 v6, 1.0, v6
	v_div_scale_f32 v7, s[8:9], v6, v6, v5
	v_rcp_f32_e32 v8, v7
	v_div_scale_f32 v9, vcc, v5, v6, v5
	v_fma_f32 v10, -v7, v8, 1.0
	v_fmac_f32_e32 v8, v10, v8
	v_mul_f32_e32 v10, v9, v8
	v_fma_f32 v11, -v7, v10, v9
	v_fmac_f32_e32 v10, v11, v8
	v_fma_f32 v7, -v7, v10, v9
	v_div_fmas_f32 v7, v7, v8, v10
	v_div_fixup_f32 v5, v7, v6, v5
	ds_write_b32 v4, v5 offset:43008
	s_waitcnt vmcnt(9)
	v_mov_b32_e32 v5, v184
	v_mul_f32_e32 v6, 0xbfb8aa3b, v5
	v_exp_f32_e32 v6, v6
	s_nop 0
	v_add_f32_e32 v6, 1.0, v6
	v_div_scale_f32 v7, s[8:9], v6, v6, v5
	v_rcp_f32_e32 v8, v7
	v_div_scale_f32 v9, vcc, v5, v6, v5
	v_fma_f32 v10, -v7, v8, 1.0
	v_fmac_f32_e32 v8, v10, v8
	v_mul_f32_e32 v10, v9, v8
	v_fma_f32 v11, -v7, v10, v9
	v_fmac_f32_e32 v10, v11, v8
	v_fma_f32 v7, -v7, v10, v9
	v_div_fmas_f32 v7, v7, v8, v10
	v_div_fixup_f32 v5, v7, v6, v5
	ds_write_b32 v4, v5 offset:45056
	s_waitcnt vmcnt(8)
; __device__ __forceinline__ void phase0(const Params& P, LAS unsigned char* lds, int G) {
;     ...
;     for (int i = tid; i < 16 * 1024; i += NTHR) { const float v = P.c[i]; sC[i] = v / (1.0f + __expf(-v)); }
	v_mov_b32_e32 v5, v185
	v_mul_f32_e32 v6, 0xbfb8aa3b, v5
	v_exp_f32_e32 v6, v6
	s_nop 0
	v_add_f32_e32 v6, 1.0, v6
	v_div_scale_f32 v7, s[8:9], v6, v6, v5
	v_rcp_f32_e32 v8, v7
	v_div_scale_f32 v9, vcc, v5, v6, v5
	v_fma_f32 v10, -v7, v8, 1.0
	v_fmac_f32_e32 v8, v10, v8
	v_mul_f32_e32 v10, v9, v8
	v_fma_f32 v11, -v7, v10, v9
	v_fmac_f32_e32 v10, v11, v8
	v_fma_f32 v7, -v7, v10, v9
	v_div_fmas_f32 v7, v7, v8, v10
	v_div_fixup_f32 v5, v7, v6, v5
	ds_write_b32 v4, v5 offset:47104
	s_waitcnt vmcnt(7)
	v_mov_b32_e32 v5, v186
	v_mul_f32_e32 v6, 0xbfb8aa3b, v5
	v_exp_f32_e32 v6, v6
	s_nop 0
	v_add_f32_e32 v6, 1.0, v6
	v_div_scale_f32 v7, s[8:9], v6, v6, v5
	v_rcp_f32_e32 v8, v7
	v_div_scale_f32 v9, vcc, v5, v6, v5
	v_fma_f32 v10, -v7, v8, 1.0
	v_fmac_f32_e32 v8, v10, v8
	v_mul_f32_e32 v10, v9, v8
	v_fma_f32 v11, -v7, v10, v9
	v_fmac_f32_e32 v10, v11, v8
	v_fma_f32 v7, -v7, v10, v9
	v_div_fmas_f32 v7, v7, v8, v10
	v_div_fixup_f32 v5, v7, v6, v5
	ds_write_b32 v4, v5 offset:49152
	s_waitcnt vmcnt(6)
	v_mov_b32_e32 v5, v187
	v_mul_f32_e32 v6, 0xbfb8aa3b, v5
	v_exp_f32_e32 v6, v6
	s_nop 0
	v_add_f32_e32 v6, 1.0, v6
	v_div_scale_f32 v7, s[8:9], v6, v6, v5
	v_rcp_f32_e32 v8, v7
	v_div_scale_f32 v9, vcc, v5, v6, v5
	v_fma_f32 v10, -v7, v8, 1.0
	v_fmac_f32_e32 v8, v10, v8
	v_mul_f32_e32 v10, v9, v8
	v_fma_f32 v11, -v7, v10, v9
	v_fmac_f32_e32 v10, v11, v8
	v_fma_f32 v7, -v7, v10, v9
	v_div_fmas_f32 v7, v7, v8, v10
	v_div_fixup_f32 v5, v7, v6, v5
	ds_write_b32 v4, v5 offset:51200
	s_waitcnt vmcnt(5)
	v_mov_b32_e32 v5, v188
	v_mul_f32_e32 v6, 0xbfb8aa3b, v5
	v_exp_f32_e32 v6, v6
	s_nop 0
	v_add_f32_e32 v6, 1.0, v6
	v_div_scale_f32 v7, s[8:9], v6, v6, v5
	v_rcp_f32_e32 v8, v7
	v_div_scale_f32 v9, vcc, v5, v6, v5
	v_fma_f32 v10, -v7, v8, 1.0
	v_fmac_f32_e32 v8, v10, v8
	v_mul_f32_e32 v10, v9, v8
	v_fma_f32 v11, -v7, v10, v9
	v_fmac_f32_e32 v10, v11, v8
	v_fma_f32 v7, -v7, v10, v9
	v_div_fmas_f32 v7, v7, v8, v10
	v_div_fixup_f32 v5, v7, v6, v5
	ds_write_b32 v4, v5 offset:53248
	s_waitcnt vmcnt(4)
	v_mov_b32_e32 v5, v189
	v_mul_f32_e32 v6, 0xbfb8aa3b, v5
	v_exp_f32_e32 v6, v6
	s_nop 0
	v_add_f32_e32 v6, 1.0, v6
	v_div_scale_f32 v7, s[8:9], v6, v6, v5
	v_rcp_f32_e32 v8, v7
	v_div_scale_f32 v9, vcc, v5, v6, v5
	v_fma_f32 v10, -v7, v8, 1.0
	v_fmac_f32_e32 v8, v10, v8
	v_mul_f32_e32 v10, v9, v8
	v_fma_f32 v11, -v7, v10, v9
	v_fmac_f32_e32 v10, v11, v8
	v_fma_f32 v7, -v7, v10, v9
	v_div_fmas_f32 v7, v7, v8, v10
	v_div_fixup_f32 v5, v7, v6, v5
	ds_write_b32 v4, v5 offset:55296
	s_waitcnt vmcnt(3)
	v_mov_b32_e32 v5, v190
	v_mul_f32_e32 v6, 0xbfb8aa3b, v5
	v_exp_f32_e32 v6, v6
	s_nop 0
	v_add_f32_e32 v6, 1.0, v6
	v_div_scale_f32 v7, s[8:9], v6, v6, v5
	v_rcp_f32_e32 v8, v7
	v_div_scale_f32 v9, vcc, v5, v6, v5
	v_fma_f32 v10, -v7, v8, 1.0
	v_fmac_f32_e32 v8, v10, v8
	v_mul_f32_e32 v10, v9, v8
	v_fma_f32 v11, -v7, v10, v9
	v_fmac_f32_e32 v10, v11, v8
	v_fma_f32 v7, -v7, v10, v9
	v_div_fmas_f32 v7, v7, v8, v10
	v_div_fixup_f32 v5, v7, v6, v5
	ds_write_b32 v4, v5 offset:57344
	s_waitcnt vmcnt(2)
	v_mov_b32_e32 v5, v191
	v_mul_f32_e32 v6, 0xbfb8aa3b, v5
	v_exp_f32_e32 v6, v6
	s_nop 0
	v_add_f32_e32 v6, 1.0, v6
	v_div_scale_f32 v7, s[8:9], v6, v6, v5
	v_rcp_f32_e32 v8, v7
	v_div_scale_f32 v9, vcc, v5, v6, v5
	v_fma_f32 v10, -v7, v8, 1.0
	v_fmac_f32_e32 v8, v10, v8
	v_mul_f32_e32 v10, v9, v8
	v_fma_f32 v11, -v7, v10, v9
	v_fmac_f32_e32 v10, v11, v8
	v_fma_f32 v7, -v7, v10, v9
	v_div_fmas_f32 v7, v7, v8, v10
	v_div_fixup_f32 v5, v7, v6, v5
	ds_write_b32 v4, v5 offset:59392
	s_waitcnt vmcnt(1)
	v_mov_b32_e32 v5, v192
	v_mul_f32_e32 v6, 0xbfb8aa3b, v5
	v_exp_f32_e32 v6, v6
	s_nop 0
	v_add_f32_e32 v6, 1.0, v6
	v_div_scale_f32 v7, s[8:9], v6, v6, v5
	v_rcp_f32_e32 v8, v7
	v_div_scale_f32 v9, vcc, v5, v6, v5
	v_fma_f32 v10, -v7, v8, 1.0
	v_fmac_f32_e32 v8, v10, v8
	v_mul_f32_e32 v10, v9, v8
	v_fma_f32 v11, -v7, v10, v9
	v_fmac_f32_e32 v10, v11, v8
	v_fma_f32 v7, -v7, v10, v9
	v_div_fmas_f32 v7, v7, v8, v10
	v_div_fixup_f32 v5, v7, v6, v5
	ds_write_b32 v4, v5 offset:61440
	s_waitcnt vmcnt(0)
	v_mov_b32_e32 v5, v193
	v_mul_f32_e32 v6, 0xbfb8aa3b, v5
	v_exp_f32_e32 v6, v6
	s_nop 0
	v_add_f32_e32 v6, 1.0, v6
	v_div_scale_f32 v7, s[8:9], v6, v6, v5
	v_rcp_f32_e32 v8, v7
	v_div_scale_f32 v9, vcc, v5, v6, v5
	v_fma_f32 v10, -v7, v8, 1.0
	v_fmac_f32_e32 v8, v10, v8
	v_mul_f32_e32 v10, v9, v8
	v_fma_f32 v11, -v7, v10, v9
	v_fmac_f32_e32 v10, v11, v8
	v_fma_f32 v7, -v7, v10, v9
	v_div_fmas_f32 v7, v7, v8, v10
	v_div_fixup_f32 v5, v7, v6, v5
	ds_write_b32 v4, v5 offset:63488
